# MIX work queue: thread 0 issues the pop atomic before the loop-head store drain and barrier so its round trip overlaps them (on top of vt_pair2)
# speedup vs baseline: 1.0135x; 1.0024x over previous
; __device__ __forceinline__ int mk_tid(int wid_s) { int t = wid_s * 64 + (int)__builtin_amdgcn_mbcnt_hi(~0u, __builtin_amdgcn_mbcnt_lo(~0u, 0u)); asm volatile("" : "+v"(t)); return t; }
; __global__ void __launch_bounds__(512, 2) fwd_kernel(Params parg) {
;     ...
;                 unsigned* ctr = ctl + q * 4 + l * 2 + r; volatile int* qidx = (volatile int*)(lds + QIDX_OFF);
;                 for (;;) {
;                     __syncthreads();
;                     if (mk_tid(wid_s) == 0) *qidx = (int)atomicAdd(ctr, 1u);
;                     __syncthreads();
;                     const int u = *qidx;
.LBB0_1420:
	v_cmp_eq_u32_e32 vcc, 0, v169
	s_and_saveexec_b64 s[2:3], vcc
	v_mov_b64_e32 v[0:1], s[6:7]
	flat_atomic_add v2, v[0:1], v170 sc0
	s_mov_b64 exec, s[2:3]
	s_waitcnt vmcnt(0)
	v_mov_b32_e32 v0, v169
	s_waitcnt lgkmcnt(0)
	s_barrier
	s_nop 0
	v_cmp_eq_u32_e32 vcc, 0, v0
	s_and_saveexec_b64 s[2:3], vcc
	s_cbranch_execz .LBB0_1422
	s_add_i32 s0, 0, 0x222e0
	s_mov_b64 s[4:5], src_shared_base
	s_cmp_lg_u32 s0, -1
	s_cselect_b32 s0, s0, 0
	s_cselect_b32 s4, s5, 0
	v_mov_b32_e32 v0, s0
	v_mov_b32_e32 v1, s4
	s_waitcnt vmcnt(0) lgkmcnt(0)
	flat_store_dword v[0:1], v2 sc0 sc1
	s_waitcnt vmcnt(0)
